# out-GEMM epilogue: ds_bpermute lane reductions replaced by v_permlane16/32_swap (bit-identical), added to FFN1 epilogue permlane reductions + DF-loop LDS pipelining + prep loop pipelining
# baseline (speedup 1.0000x reference)
; __device__ __forceinline__ u32x4 pack8(const float* v) { u32x4 w; w.x = cvt_pk_bf16(v[0], v[1]); w.y = cvt_pk_bf16(v[2], v[3]); w.z = cvt_pk_bf16(v[4], v[5]); w.w = cvt_pk_bf16(v[6], v[7]); return w; }
; #define PG8_GATHER(ai, m) float a[8], b[8]; _Pragma("unroll") for (int j = 0; j < 4; ++j) { a[j] = acc[ai][0][m][0][j]; a[4 + j] = acc[ai][0][m][1][j]; b[j] = acc[ai][1][m][0][j]; b[4 + j] = acc[ai][1][m][1][j]; }
;     __device__ __forceinline__ float finish_ss(int row, int pn, int within, const float* a, const float* b, const Pre& p, const f32x4* g) const {
;         const int c = pn * 256 + within; float ss = 0.f;
; #pragma unroll
;         for (int hb = 0; hb < 2; ++hb) { const float* v = hb ? b : a; const int cc = c + hb * 128; f32x4 h0, h1; float o[8];
; #pragma unroll
;             for (int j = 0; j < 4; ++j) { h0[j] = p.x[2 * hb][j] + v[j]; h1[j] = p.x[2 * hb + 1][j] + v[4 + j]; ss += h0[j] * h0[j] + h1[j] * h1[j]; o[j] = h0[j] * g[2 * hb][j]; o[4 + j] = h1[j] * g[2 * hb + 1][j]; }
;             float hh[8] = {h0[0], h0[1], h0[2], h0[3], h1[0], h1[1], h1[2], h1[3]};
;             *(u32x4*)(hcopy + (size_t)row * DM + cc) = pack8(hh);
;             *(u32x4*)(hg + (size_t)row * DM + cc) = pack8(o); }
;         return ss;
;     }
; __device__ __forceinline__ void run_epi_out(const EpiOut& E, float* ssq, const f32x4 (&acc)[2][2][4][2], const Unit& u, int wr, int wc, int fr, int fq) {
;     asm volatile("" : "+v"(fr), "+v"(fq));
;     const int within = wc * 32 + fq * 8; const float* gp = E.g2 + u.pn * 256 + within;
;     const f32x4 g[4] = {*(const f32x4*)gp, *(const f32x4*)(gp + 4), *(const f32x4*)(gp + 128), *(const f32x4*)(gp + 132)};
; #pragma unroll
;     for (int ai = 0; ai < 2; ++ai) { const int row0 = u.pm * BM + ai * HALF + wr * 64 + fr; EpiOut::Pre pre[4];
; #pragma unroll
;         for (int m = 0; m < 4; ++m) pre[m] = E.preload(row0 + m * 16, u.pn, within, fq);
; #pragma unroll
;         for (int m = 0; m < 4; ++m) { PG8_GATHER(ai, m); float ss = E.finish_ss(row0 + m * 16, u.pn, within, a, b, pre[m], g);
;             ss += __shfl_xor(ss, 16); ss += __shfl_xor(ss, 32);
;             if (fq == 0) ssq[(size_t)(row0 + m * 16) * 32 + u.pn * 4 + wc] = ss; } }
.LBB0_510:
	s_lshl_b32 s28, s24, 8
	s_ashr_i32 s29, s28, 31
	s_lshl_b64 s[30:31], s[28:29], 2
	s_add_u32 s34, s66, s30
	s_addc_u32 s35, s67, s31
	s_lshl_b32 s24, s24, 2
	s_lshl_b32 s17, s26, 8
	s_ashr_i32 s25, s24, 31
	s_add_i32 s17, s17, s46
	s_lshl_b64 s[24:25], s[24:25], 2
	v_mov_b32_e32 v102, v220
	v_mov_b32_e32 v204, v221
	s_add_u32 s24, s50, s24
	s_addc_u32 s25, s51, s25
	v_lshl_add_u32 v208, v204, 3, s47
	v_ashrrev_i32_e32 v209, 31, v208
	v_add_u32_e32 v210, s17, v102
	s_add_u32 s26, s40, s30
	v_lshlrev_b64 v[100:101], 2, v[208:209]
	s_addc_u32 s27, s41, s31
	v_ashrrev_i32_e32 v211, 31, v210
	v_lshl_add_u64 v[212:213], s[26:27], 0, v[100:101]
	v_lshlrev_b64 v[102:103], 13, v[210:211]
	v_lshl_add_u64 v[102:103], v[212:213], 0, v[102:103]
	global_load_dwordx4 v[230:233], v[102:103], off
	global_load_dwordx4 v[234:237], v[102:103], off offset:16
	v_lshl_add_u64 v[100:101], s[34:35], 0, v[100:101]
	global_load_dwordx4 v[116:119], v[100:101], off
	global_load_dwordx4 v[112:115], v[100:101], off offset:16
	global_load_dwordx4 v[238:241], v[102:103], off offset:512
	global_load_dwordx4 v[104:107], v[100:101], off offset:512
	global_load_dwordx4 v[242:245], v[102:103], off offset:528
	s_nop 0
	global_load_dwordx4 v[100:103], v[100:101], off offset:528
	v_add_u32_e32 v218, 16, v210
	v_add_u32_e32 v216, 32, v210
	v_add_u32_e32 v214, 48, v210
	v_ashrrev_i32_e32 v219, 31, v218
	v_ashrrev_i32_e32 v217, 31, v216
	v_ashrrev_i32_e32 v215, 31, v214
	v_lshlrev_b64 v[144:145], 13, v[218:219]
	v_lshlrev_b64 v[146:147], 13, v[216:217]
	v_lshlrev_b64 v[148:149], 13, v[214:215]
	v_lshl_add_u64 v[144:145], v[212:213], 0, v[144:145]
	v_lshl_add_u64 v[146:147], v[212:213], 0, v[146:147]
	v_lshl_add_u64 v[148:149], v[212:213], 0, v[148:149]
	global_load_dwordx4 v[184:187], v[144:145], off offset:16
	global_load_dwordx4 v[188:191], v[144:145], off
	global_load_dwordx4 v[176:179], v[144:145], off offset:528
	global_load_dwordx4 v[180:183], v[144:145], off offset:512
	global_load_dwordx4 v[168:171], v[146:147], off offset:16
	global_load_dwordx4 v[172:175], v[146:147], off
	global_load_dwordx4 v[160:163], v[146:147], off offset:528
	global_load_dwordx4 v[164:167], v[146:147], off offset:512
	global_load_dwordx4 v[152:155], v[148:149], off offset:16
	global_load_dwordx4 v[156:159], v[148:149], off
	s_nop 0
	global_load_dwordx4 v[144:147], v[148:149], off offset:528
	s_nop 0
	global_load_dwordx4 v[148:151], v[148:149], off offset:512
	v_and_b32_e32 v209, 64, v226
	v_xor_b32_e32 v205, 16, v226
	v_add_u32_e32 v209, 64, v209
	v_xor_b32_e32 v227, 32, v226
	v_cmp_lt_i32_e32 vcc, v205, v209
	v_add_u32_e32 v208, s28, v208
	v_lshlrev_b64 v[246:247], 12, v[210:211]
	v_cndmask_b32_e32 v205, v226, v205, vcc
	v_cmp_lt_i32_e32 vcc, v227, v209
	v_lshl_add_u64 v[248:249], s[10:11], 0, v[246:247]
	v_lshlrev_b32_e32 v228, 2, v205
	v_cndmask_b32_e32 v209, v226, v227, vcc
	v_lshlrev_b32_e32 v227, 2, v209
	v_ashrrev_i32_e32 v209, 31, v208
	v_lshlrev_b64 v[208:209], 1, v[208:209]
	v_cmp_eq_u32_e32 vcc, 0, v204
	v_lshl_add_u64 v[248:249], v[248:249], 0, v[208:209]
	s_waitcnt vmcnt(0)
	v_pk_add_f32 v[132:133], v[132:133], v[238:239]
	v_pk_add_f32 v[142:143], v[142:143], v[232:233]
	v_pk_add_f32 v[140:141], v[140:141], v[230:231]
	v_pk_add_f32 v[230:231], v[138:139], v[236:237]
	v_pk_add_f32 v[138:139], v[136:137], v[234:235]
	v_pk_mul_f32 v[204:205], v[114:115], v[230:231]
	v_pk_mul_f32 v[236:237], v[138:139], v[138:139]
	v_pk_mul_f32 v[250:251], v[112:113], v[138:139]
	v_cvt_pk_bf16_f32 v136, v140, v141
	v_cvt_pk_bf16_f32 v137, v142, v143
	v_cvt_pk_bf16_f32 v138, v138, v139
	v_cvt_pk_bf16_f32 v139, v230, v231
	v_pk_mul_f32 v[232:233], v[116:117], v[140:141]
	v_pk_mul_f32 v[252:253], v[118:119], v[142:143]
	global_store_dwordx4 v[248:249], v[136:139], off
	v_pk_mul_f32 v[234:235], v[230:231], v[230:231]
	v_pk_fma_f32 v[140:141], v[140:141], v[140:141], v[236:237]
	v_cvt_pk_bf16_f32 v139, v204, v205
	v_lshl_add_u64 v[204:205], s[8:9], 0, v[246:247]
	v_cvt_pk_bf16_f32 v136, v232, v233
	v_cvt_pk_bf16_f32 v137, v252, v253
	v_cvt_pk_bf16_f32 v138, v250, v251
	v_lshl_add_u64 v[204:205], v[204:205], 0, v[208:209]
	v_pk_fma_f32 v[142:143], v[142:143], v[142:143], v[234:235]
	global_store_dwordx4 v[204:205], v[136:139], off
	v_add_f32_e32 v140, v140, v141
	v_add_f32_e32 v140, v142, v140
	v_pk_add_f32 v[138:139], v[130:131], v[244:245]
	v_pk_add_f32 v[130:131], v[128:129], v[242:243]
	v_add_f32_e32 v140, v143, v140
	v_pk_mul_f32 v[230:231], v[130:131], v[130:131]
	v_pk_add_f32 v[134:135], v[134:135], v[240:241]
	v_pk_fma_f32 v[230:231], v[132:133], v[132:133], v[230:231]
	v_pk_mul_f32 v[128:129], v[138:139], v[138:139]
	v_add_f32_e32 v140, v230, v140
	v_pk_fma_f32 v[128:129], v[134:135], v[134:135], v[128:129]
	v_add_f32_e32 v140, v231, v140
	v_add_f32_e32 v128, v128, v140
	v_add_f32_e32 v142, v129, v128
	v_pk_mul_f32 v[136:137], v[104:105], v[132:133]
	v_cvt_pk_bf16_f32 v128, v132, v133
	ds_bpermute_b32 v132, v228, v142
	v_pk_mul_f32 v[232:233], v[100:101], v[130:131]
	v_cvt_pk_bf16_f32 v129, v134, v135
	v_cvt_pk_bf16_f32 v130, v130, v131
	v_cvt_pk_bf16_f32 v131, v138, v139
	global_store_dwordx4 v[248:249], v[128:131], off offset:256
	v_pk_mul_f32 v[234:235], v[106:107], v[134:135]
	v_pk_mul_f32 v[140:141], v[102:103], v[138:139]
	s_waitcnt lgkmcnt(0)
	v_add_f32_e32 v128, v142, v132
	v_mov_b32_e32 v129, v128
	s_nop 1
	v_permlane32_swap_b32_e32 v129, v128
	v_cvt_pk_bf16_f32 v130, v136, v137
	v_cvt_pk_bf16_f32 v131, v234, v235
	v_cvt_pk_bf16_f32 v132, v232, v233
	v_cvt_pk_bf16_f32 v133, v140, v141
	global_store_dwordx4 v[204:205], v[130:133], off offset:256
	s_and_saveexec_b64 s[26:27], vcc
	s_cbranch_execz .LBB0_512
	v_lshlrev_b64 v[130:131], 7, v[210:211]
	v_lshl_add_u64 v[130:131], s[24:25], 0, v[130:131]
	s_waitcnt lgkmcnt(0)
	v_add_f32_e32 v128, v128, v129
	global_store_dword v[130:131], v128, off
; __device__ __forceinline__ u32x4 pack8(const float* v) { u32x4 w; w.x = cvt_pk_bf16(v[0], v[1]); w.y = cvt_pk_bf16(v[2], v[3]); w.z = cvt_pk_bf16(v[4], v[5]); w.w = cvt_pk_bf16(v[6], v[7]); return w; }
; #define PG8_GATHER(ai, m) float a[8], b[8]; _Pragma("unroll") for (int j = 0; j < 4; ++j) { a[j] = acc[ai][0][m][0][j]; a[4 + j] = acc[ai][0][m][1][j]; b[j] = acc[ai][1][m][0][j]; b[4 + j] = acc[ai][1][m][1][j]; }
;     __device__ __forceinline__ float finish_ss(int row, int pn, int within, const float* a, const float* b, const Pre& p, const f32x4* g) const {
;     ...
;             for (int j = 0; j < 4; ++j) { h0[j] = p.x[2 * hb][j] + v[j]; h1[j] = p.x[2 * hb + 1][j] + v[4 + j]; ss += h0[j] * h0[j] + h1[j] * h1[j]; o[j] = h0[j] * g[2 * hb][j]; o[4 + j] = h1[j] * g[2 * hb + 1][j]; }
;             float hh[8] = {h0[0], h0[1], h0[2], h0[3], h1[0], h1[1], h1[2], h1[3]};
;             *(u32x4*)(hcopy + (size_t)row * DM + cc) = pack8(hh);
;             *(u32x4*)(hg + (size_t)row * DM + cc) = pack8(o); }
;         return ss;
; __device__ __forceinline__ void run_epi_out(const EpiOut& E, float* ssq, const f32x4 (&acc)[2][2][4][2], const Unit& u, int wr, int wc, int fr, int fq) {
;     ...
;         for (int m = 0; m < 4; ++m) { PG8_GATHER(ai, m); float ss = E.finish_ss(row0 + m * 16, u.pn, within, a, b, pre[m], g);
;             ss += __shfl_xor(ss, 16); ss += __shfl_xor(ss, 32);
;             if (fq == 0) ssq[(size_t)(row0 + m * 16) * 32 + u.pn * 4 + wc] = ss; } }
.LBB0_512:
	s_or_b64 exec, exec, s[26:27]
	v_pk_add_f32 v[130:131], v[122:123], v[186:187]
	v_pk_add_f32 v[122:123], v[120:121], v[184:185]
	v_pk_add_f32 v[126:127], v[126:127], v[190:191]
	v_pk_add_f32 v[124:125], v[124:125], v[188:189]
	v_pk_mul_f32 v[120:121], v[130:131], v[130:131]
	v_pk_mul_f32 v[132:133], v[122:123], v[122:123]
	s_waitcnt lgkmcnt(0)
	v_pk_mul_f32 v[128:129], v[116:117], v[124:125]
	v_pk_fma_f32 v[134:135], v[126:127], v[126:127], v[120:121]
	v_pk_fma_f32 v[132:133], v[124:125], v[124:125], v[132:133]
	v_cvt_pk_bf16_f32 v120, v124, v125
	v_lshlrev_b64 v[124:125], 12, v[218:219]
	v_pk_mul_f32 v[138:139], v[118:119], v[126:127]
	v_cvt_pk_bf16_f32 v121, v126, v127
	v_lshl_add_u64 v[126:127], s[10:11], 0, v[124:125]
	v_pk_mul_f32 v[136:137], v[112:113], v[122:123]
	v_pk_mul_f32 v[140:141], v[114:115], v[130:131]
	v_cvt_pk_bf16_f32 v122, v122, v123
	v_cvt_pk_bf16_f32 v123, v130, v131
	v_lshl_add_u64 v[126:127], v[126:127], 0, v[208:209]
	v_lshl_add_u64 v[124:125], s[8:9], 0, v[124:125]
	global_store_dwordx4 v[126:127], v[120:123], off
	v_lshl_add_u64 v[124:125], v[124:125], 0, v[208:209]
	v_add_f32_e32 v132, v132, v133
	v_cvt_pk_bf16_f32 v120, v128, v129
	v_cvt_pk_bf16_f32 v121, v138, v139
	v_cvt_pk_bf16_f32 v122, v136, v137
	v_cvt_pk_bf16_f32 v123, v140, v141
	global_store_dwordx4 v[124:125], v[120:123], off
	v_pk_add_f32 v[108:109], v[108:109], v[180:181]
	v_add_f32_e32 v132, v134, v132
	v_pk_add_f32 v[122:123], v[98:99], v[178:179]
	v_pk_add_f32 v[98:99], v[96:97], v[176:177]
	v_add_f32_e32 v132, v135, v132
	v_pk_mul_f32 v[128:129], v[98:99], v[98:99]
	v_pk_add_f32 v[110:111], v[110:111], v[182:183]
	v_pk_fma_f32 v[128:129], v[108:109], v[108:109], v[128:129]
	v_pk_mul_f32 v[96:97], v[122:123], v[122:123]
	v_add_f32_e32 v128, v128, v132
	v_pk_fma_f32 v[96:97], v[110:111], v[110:111], v[96:97]
	v_add_f32_e32 v128, v129, v128
	v_add_f32_e32 v96, v96, v128
	v_add_f32_e32 v132, v97, v96
	v_pk_mul_f32 v[120:121], v[104:105], v[108:109]
	v_cvt_pk_bf16_f32 v96, v108, v109
	v_mov_b32_e32 v109, v132
	s_nop 1
	v_permlane16_swap_b32_e32 v109, v132
	v_pk_mul_f32 v[130:131], v[100:101], v[98:99]
	v_cvt_pk_bf16_f32 v97, v110, v111
	v_cvt_pk_bf16_f32 v98, v98, v99
	v_cvt_pk_bf16_f32 v99, v122, v123
	global_store_dwordx4 v[126:127], v[96:99], off offset:256
	v_pk_mul_f32 v[136:137], v[106:107], v[110:111]
	v_pk_mul_f32 v[128:129], v[102:103], v[122:123]
	s_waitcnt lgkmcnt(0)
	v_add_f32_e32 v96, v132, v109
	v_mov_b32_e32 v97, v96
	s_nop 1
	v_permlane32_swap_b32_e32 v97, v96
	v_cvt_pk_bf16_f32 v108, v120, v121
	v_cvt_pk_bf16_f32 v109, v136, v137
	v_cvt_pk_bf16_f32 v110, v130, v131
	v_cvt_pk_bf16_f32 v111, v128, v129
	global_store_dwordx4 v[124:125], v[108:111], off offset:256
	s_and_saveexec_b64 s[26:27], vcc
	s_cbranch_execz .LBB0_514
	v_lshlrev_b64 v[98:99], 7, v[218:219]
	v_lshl_add_u64 v[98:99], s[24:25], 0, v[98:99]
	s_waitcnt lgkmcnt(0)
	v_add_f32_e32 v96, v96, v97
	global_store_dword v[98:99], v96, off
.LBB0_514:
	s_or_b64 exec, exec, s[26:27]
	v_pk_add_f32 v[98:99], v[90:91], v[170:171]
	v_pk_add_f32 v[90:91], v[88:89], v[168:169]
	v_pk_add_f32 v[94:95], v[94:95], v[174:175]
	v_pk_add_f32 v[92:93], v[92:93], v[172:173]
	v_pk_mul_f32 v[88:89], v[98:99], v[98:99]
	v_pk_mul_f32 v[108:109], v[90:91], v[90:91]
	s_waitcnt lgkmcnt(0)
	v_pk_mul_f32 v[96:97], v[116:117], v[92:93]
	v_pk_fma_f32 v[110:111], v[94:95], v[94:95], v[88:89]
	v_pk_fma_f32 v[108:109], v[92:93], v[92:93], v[108:109]
	v_cvt_pk_bf16_f32 v88, v92, v93
	v_lshlrev_b64 v[92:93], 12, v[216:217]
	v_pk_mul_f32 v[122:123], v[118:119], v[94:95]
	v_cvt_pk_bf16_f32 v89, v94, v95
	v_lshl_add_u64 v[94:95], s[10:11], 0, v[92:93]
	v_pk_mul_f32 v[120:121], v[112:113], v[90:91]
	v_pk_mul_f32 v[124:125], v[114:115], v[98:99]
	v_cvt_pk_bf16_f32 v90, v90, v91
	v_cvt_pk_bf16_f32 v91, v98, v99
	v_lshl_add_u64 v[94:95], v[94:95], 0, v[208:209]
	v_lshl_add_u64 v[92:93], s[8:9], 0, v[92:93]
	global_store_dwordx4 v[94:95], v[88:91], off
	v_lshl_add_u64 v[92:93], v[92:93], 0, v[208:209]
	v_add_f32_e32 v108, v108, v109
	v_cvt_pk_bf16_f32 v88, v96, v97
	v_cvt_pk_bf16_f32 v89, v122, v123
	v_cvt_pk_bf16_f32 v90, v120, v121
	v_cvt_pk_bf16_f32 v91, v124, v125
	global_store_dwordx4 v[92:93], v[88:91], off
	v_pk_add_f32 v[84:85], v[84:85], v[164:165]
	v_add_f32_e32 v108, v110, v108
	v_pk_add_f32 v[90:91], v[82:83], v[162:163]
	v_pk_add_f32 v[82:83], v[80:81], v[160:161]
	v_add_f32_e32 v108, v111, v108
	v_pk_mul_f32 v[96:97], v[82:83], v[82:83]
	v_pk_add_f32 v[86:87], v[86:87], v[166:167]
	v_pk_fma_f32 v[96:97], v[84:85], v[84:85], v[96:97]
	v_pk_mul_f32 v[80:81], v[90:91], v[90:91]
	v_add_f32_e32 v96, v96, v108
	v_pk_fma_f32 v[80:81], v[86:87], v[86:87], v[80:81]
	v_add_f32_e32 v96, v97, v96
	v_add_f32_e32 v80, v80, v96
	v_add_f32_e32 v108, v81, v80
	v_pk_mul_f32 v[88:89], v[104:105], v[84:85]
	v_cvt_pk_bf16_f32 v80, v84, v85
	v_mov_b32_e32 v84, v108
	s_nop 1
	v_permlane16_swap_b32_e32 v84, v108
	v_pk_mul_f32 v[98:99], v[100:101], v[82:83]
	v_cvt_pk_bf16_f32 v81, v86, v87
	v_cvt_pk_bf16_f32 v82, v82, v83
	v_cvt_pk_bf16_f32 v83, v90, v91
	global_store_dwordx4 v[94:95], v[80:83], off offset:256
	v_pk_mul_f32 v[120:121], v[106:107], v[86:87]
	v_pk_mul_f32 v[96:97], v[102:103], v[90:91]
	s_waitcnt lgkmcnt(0)
	v_add_f32_e32 v80, v108, v84
	v_mov_b32_e32 v81, v80
	s_nop 1
	v_permlane32_swap_b32_e32 v81, v80
	v_cvt_pk_bf16_f32 v82, v88, v89
	v_cvt_pk_bf16_f32 v83, v120, v121
	v_cvt_pk_bf16_f32 v84, v98, v99
	v_cvt_pk_bf16_f32 v85, v96, v97
	global_store_dwordx4 v[92:93], v[82:85], off offset:256
	s_and_saveexec_b64 s[26:27], vcc
	s_cbranch_execz .LBB0_516
	v_lshlrev_b64 v[82:83], 7, v[216:217]
	v_lshl_add_u64 v[82:83], s[24:25], 0, v[82:83]
	s_waitcnt lgkmcnt(0)
	v_add_f32_e32 v80, v80, v81
	global_store_dword v[82:83], v80, off
; __device__ __forceinline__ u32x4 pack8(const float* v) { u32x4 w; w.x = cvt_pk_bf16(v[0], v[1]); w.y = cvt_pk_bf16(v[2], v[3]); w.z = cvt_pk_bf16(v[4], v[5]); w.w = cvt_pk_bf16(v[6], v[7]); return w; }
; #define PG8_GATHER(ai, m) float a[8], b[8]; _Pragma("unroll") for (int j = 0; j < 4; ++j) { a[j] = acc[ai][0][m][0][j]; a[4 + j] = acc[ai][0][m][1][j]; b[j] = acc[ai][1][m][0][j]; b[4 + j] = acc[ai][1][m][1][j]; }
;     __device__ __forceinline__ float finish_ss(int row, int pn, int within, const float* a, const float* b, const Pre& p, const f32x4* g) const {
;         const int c = pn * 256 + within; float ss = 0.f;
; #pragma unroll
;         for (int hb = 0; hb < 2; ++hb) { const float* v = hb ? b : a; const int cc = c + hb * 128; f32x4 h0, h1; float o[8];
; #pragma unroll
;             for (int j = 0; j < 4; ++j) { h0[j] = p.x[2 * hb][j] + v[j]; h1[j] = p.x[2 * hb + 1][j] + v[4 + j]; ss += h0[j] * h0[j] + h1[j] * h1[j]; o[j] = h0[j] * g[2 * hb][j]; o[4 + j] = h1[j] * g[2 * hb + 1][j]; }
;             float hh[8] = {h0[0], h0[1], h0[2], h0[3], h1[0], h1[1], h1[2], h1[3]};
;             *(u32x4*)(hcopy + (size_t)row * DM + cc) = pack8(hh);
;             *(u32x4*)(hg + (size_t)row * DM + cc) = pack8(o); }
;         return ss;
; __device__ __forceinline__ void run_epi_out(const EpiOut& E, float* ssq, const f32x4 (&acc)[2][2][4][2], const Unit& u, int wr, int wc, int fr, int fq) {
;     ...
;         for (int m = 0; m < 4; ++m) pre[m] = E.preload(row0 + m * 16, u.pn, within, fq);
; #pragma unroll
;         for (int m = 0; m < 4; ++m) { PG8_GATHER(ai, m); float ss = E.finish_ss(row0 + m * 16, u.pn, within, a, b, pre[m], g);
;             ss += __shfl_xor(ss, 16); ss += __shfl_xor(ss, 32);
;             if (fq == 0) ssq[(size_t)(row0 + m * 16) * 32 + u.pn * 4 + wc] = ss; } }
.LBB0_516:
	s_or_b64 exec, exec, s[26:27]
	v_pk_add_f32 v[82:83], v[74:75], v[154:155]
	v_pk_add_f32 v[74:75], v[72:73], v[152:153]
	v_pk_add_f32 v[78:79], v[78:79], v[158:159]
	v_pk_add_f32 v[76:77], v[76:77], v[156:157]
	v_pk_mul_f32 v[72:73], v[82:83], v[82:83]
	v_pk_mul_f32 v[84:85], v[74:75], v[74:75]
	s_waitcnt lgkmcnt(0)
	v_pk_mul_f32 v[80:81], v[116:117], v[76:77]
	v_pk_fma_f32 v[86:87], v[78:79], v[78:79], v[72:73]
	v_pk_fma_f32 v[84:85], v[76:77], v[76:77], v[84:85]
	v_cvt_pk_bf16_f32 v72, v76, v77
	v_lshlrev_b64 v[76:77], 12, v[214:215]
	v_pk_mul_f32 v[90:91], v[118:119], v[78:79]
	v_cvt_pk_bf16_f32 v73, v78, v79
	v_lshl_add_u64 v[78:79], s[10:11], 0, v[76:77]
	v_pk_mul_f32 v[88:89], v[112:113], v[74:75]
	v_pk_mul_f32 v[92:93], v[114:115], v[82:83]
	v_cvt_pk_bf16_f32 v74, v74, v75
	v_cvt_pk_bf16_f32 v75, v82, v83
	v_lshl_add_u64 v[78:79], v[78:79], 0, v[208:209]
	v_lshl_add_u64 v[76:77], s[8:9], 0, v[76:77]
	global_store_dwordx4 v[78:79], v[72:75], off
	v_lshl_add_u64 v[76:77], v[76:77], 0, v[208:209]
	v_add_f32_e32 v84, v84, v85
	v_cvt_pk_bf16_f32 v72, v80, v81
	v_cvt_pk_bf16_f32 v73, v90, v91
	v_cvt_pk_bf16_f32 v74, v88, v89
	v_cvt_pk_bf16_f32 v75, v92, v93
	global_store_dwordx4 v[76:77], v[72:75], off
	v_pk_add_f32 v[68:69], v[68:69], v[148:149]
	v_add_f32_e32 v84, v86, v84
	v_pk_add_f32 v[74:75], v[66:67], v[146:147]
	v_pk_add_f32 v[66:67], v[64:65], v[144:145]
	v_add_f32_e32 v84, v87, v84
	v_pk_mul_f32 v[80:81], v[66:67], v[66:67]
	v_pk_add_f32 v[70:71], v[70:71], v[150:151]
	v_pk_fma_f32 v[80:81], v[68:69], v[68:69], v[80:81]
	v_pk_mul_f32 v[64:65], v[74:75], v[74:75]
	v_add_f32_e32 v80, v80, v84
	v_pk_fma_f32 v[64:65], v[70:71], v[70:71], v[64:65]
	v_add_f32_e32 v80, v81, v80
	v_add_f32_e32 v64, v64, v80
	v_add_f32_e32 v84, v65, v64
	v_pk_mul_f32 v[72:73], v[104:105], v[68:69]
	v_cvt_pk_bf16_f32 v64, v68, v69
	v_mov_b32_e32 v68, v84
	s_nop 1
	v_permlane16_swap_b32_e32 v68, v84
	v_pk_mul_f32 v[82:83], v[100:101], v[66:67]
	v_cvt_pk_bf16_f32 v65, v70, v71
	v_cvt_pk_bf16_f32 v66, v66, v67
	v_cvt_pk_bf16_f32 v67, v74, v75
	global_store_dwordx4 v[78:79], v[64:67], off offset:256
	v_pk_mul_f32 v[88:89], v[106:107], v[70:71]
	v_pk_mul_f32 v[80:81], v[102:103], v[74:75]
	s_waitcnt lgkmcnt(0)
	v_add_f32_e32 v64, v84, v68
	v_mov_b32_e32 v65, v64
	s_nop 1
	v_permlane32_swap_b32_e32 v65, v64
	v_cvt_pk_bf16_f32 v66, v72, v73
	v_cvt_pk_bf16_f32 v67, v88, v89
	v_cvt_pk_bf16_f32 v68, v82, v83
	v_cvt_pk_bf16_f32 v69, v80, v81
	global_store_dwordx4 v[76:77], v[66:69], off offset:256
	s_and_saveexec_b64 s[26:27], vcc
	s_cbranch_execz .LBB0_518
	v_lshlrev_b64 v[66:67], 7, v[214:215]
	v_lshl_add_u64 v[66:67], s[24:25], 0, v[66:67]
	s_waitcnt lgkmcnt(0)
	v_add_f32_e32 v64, v64, v65
	global_store_dword v[66:67], v64, off
.LBB0_518:
	s_or_b64 exec, exec, s[26:27]
	v_add_u32_e32 v134, 0x80, v210
	v_ashrrev_i32_e32 v135, 31, v134
	s_waitcnt lgkmcnt(0)
	v_lshlrev_b64 v[64:65], 13, v[134:135]
	v_lshl_add_u64 v[64:65], v[212:213], 0, v[64:65]
	global_load_dwordx4 v[136:139], v[64:65], off
	global_load_dwordx4 v[140:143], v[64:65], off offset:16
	global_load_dwordx4 v[144:147], v[64:65], off offset:512
	global_load_dwordx4 v[148:151], v[64:65], off offset:528
	v_add_u32_e32 v132, 0x90, v210
	v_add_u32_e32 v130, 0xa0, v210
	v_add_u32_e32 v128, 0xb0, v210
	v_ashrrev_i32_e32 v133, 31, v132
	v_ashrrev_i32_e32 v131, 31, v130
	v_ashrrev_i32_e32 v129, 31, v128
	v_lshlrev_b64 v[64:65], 13, v[132:133]
	v_lshlrev_b64 v[66:67], 13, v[130:131]
	v_lshlrev_b64 v[68:69], 13, v[128:129]
	v_lshl_add_u64 v[64:65], v[212:213], 0, v[64:65]
	v_lshl_add_u64 v[66:67], v[212:213], 0, v[66:67]
	v_lshl_add_u64 v[68:69], v[212:213], 0, v[68:69]
	global_load_dwordx4 v[120:123], v[64:65], off offset:16
	global_load_dwordx4 v[124:127], v[64:65], off
	global_load_dwordx4 v[96:99], v[64:65], off offset:528
	global_load_dwordx4 v[108:111], v[64:65], off offset:512
	global_load_dwordx4 v[88:91], v[66:67], off offset:16
	global_load_dwordx4 v[92:95], v[66:67], off
	global_load_dwordx4 v[80:83], v[66:67], off offset:528
	global_load_dwordx4 v[84:87], v[66:67], off offset:512
	global_load_dwordx4 v[72:75], v[68:69], off offset:16
	global_load_dwordx4 v[76:79], v[68:69], off
	s_nop 0
	global_load_dwordx4 v[64:67], v[68:69], off offset:528
	s_nop 0
	global_load_dwordx4 v[68:71], v[68:69], off offset:512
	v_lshlrev_b64 v[152:153], 12, v[134:135]
	v_lshl_add_u64 v[154:155], s[10:11], 0, v[152:153]
	v_lshl_add_u64 v[152:153], s[8:9], 0, v[152:153]
	v_lshl_add_u64 v[154:155], v[154:155], 0, v[208:209]
	v_lshl_add_u64 v[152:153], v[152:153], 0, v[208:209]
	s_waitcnt vmcnt(15)
	v_pk_add_f32 v[62:63], v[62:63], v[138:139]
	v_pk_add_f32 v[60:61], v[60:61], v[136:137]
	s_waitcnt vmcnt(14)
	v_pk_add_f32 v[58:59], v[58:59], v[142:143]
	v_pk_add_f32 v[56:57], v[56:57], v[140:141]
	s_waitcnt vmcnt(13)
	v_pk_add_f32 v[54:55], v[54:55], v[146:147]
	s_waitcnt vmcnt(12)
	v_pk_add_f32 v[138:139], v[50:51], v[150:151]
	v_pk_add_f32 v[140:141], v[48:49], v[148:149]
	v_pk_mul_f32 v[142:143], v[116:117], v[60:61]
	v_pk_mul_f32 v[146:147], v[56:57], v[56:57]
	v_pk_mul_f32 v[148:149], v[112:113], v[56:57]
	v_pk_mul_f32 v[150:151], v[118:119], v[62:63]
	v_pk_mul_f32 v[156:157], v[114:115], v[58:59]
	v_cvt_pk_bf16_f32 v48, v60, v61
	v_cvt_pk_bf16_f32 v49, v62, v63
	v_cvt_pk_bf16_f32 v50, v56, v57
	v_cvt_pk_bf16_f32 v51, v58, v59
	v_pk_add_f32 v[136:137], v[52:53], v[144:145]
	v_pk_mul_f32 v[144:145], v[58:59], v[58:59]
	v_pk_fma_f32 v[60:61], v[60:61], v[60:61], v[146:147]
	global_store_dwordx4 v[154:155], v[48:51], off
	v_pk_fma_f32 v[62:63], v[62:63], v[62:63], v[144:145]
	v_pk_mul_f32 v[158:159], v[140:141], v[140:141]
	v_cvt_pk_bf16_f32 v48, v142, v143
	v_cvt_pk_bf16_f32 v49, v150, v151
	v_cvt_pk_bf16_f32 v50, v148, v149
	v_cvt_pk_bf16_f32 v51, v156, v157
	global_store_dwordx4 v[152:153], v[48:51], off
	v_pk_mul_f32 v[56:57], v[104:105], v[136:137]
	v_cvt_pk_bf16_f32 v52, v136, v137
	v_add_f32_e32 v48, v60, v61
	v_add_f32_e32 v48, v62, v48
	v_pk_fma_f32 v[136:137], v[136:137], v[136:137], v[158:159]
	v_add_f32_e32 v48, v63, v48
	v_pk_mul_f32 v[58:59], v[138:139], v[138:139]
	v_add_f32_e32 v48, v136, v48
	v_pk_fma_f32 v[58:59], v[54:55], v[54:55], v[58:59]
	v_add_f32_e32 v48, v137, v48
	v_add_f32_e32 v48, v58, v48
	v_add_f32_e32 v48, v59, v48
	v_mov_b32_e32 v49, v48
	s_nop 1
	v_permlane16_swap_b32_e32 v49, v48
	v_pk_mul_f32 v[160:161], v[100:101], v[140:141]
	v_pk_mul_f32 v[162:163], v[106:107], v[54:55]
	v_pk_mul_f32 v[164:165], v[102:103], v[138:139]
	v_cvt_pk_bf16_f32 v53, v54, v55
	s_waitcnt lgkmcnt(0)
	v_add_f32_e32 v48, v48, v49
	v_mov_b32_e32 v49, v48
	s_nop 1
	v_permlane32_swap_b32_e32 v49, v48
	v_cvt_pk_bf16_f32 v54, v140, v141
	v_cvt_pk_bf16_f32 v55, v138, v139
	global_store_dwordx4 v[154:155], v[52:55], off offset:256
	v_cvt_pk_bf16_f32 v50, v56, v57
	v_cvt_pk_bf16_f32 v51, v162, v163
	v_cvt_pk_bf16_f32 v52, v160, v161
	v_cvt_pk_bf16_f32 v53, v164, v165
	global_store_dwordx4 v[152:153], v[50:53], off offset:256
	s_and_saveexec_b64 s[26:27], vcc
	s_cbranch_execz .LBB0_520
; __device__ __forceinline__ u32x4 pack8(const float* v) { u32x4 w; w.x = cvt_pk_bf16(v[0], v[1]); w.y = cvt_pk_bf16(v[2], v[3]); w.z = cvt_pk_bf16(v[4], v[5]); w.w = cvt_pk_bf16(v[6], v[7]); return w; }
; #define PG8_GATHER(ai, m) float a[8], b[8]; _Pragma("unroll") for (int j = 0; j < 4; ++j) { a[j] = acc[ai][0][m][0][j]; a[4 + j] = acc[ai][0][m][1][j]; b[j] = acc[ai][1][m][0][j]; b[4 + j] = acc[ai][1][m][1][j]; }
;     __device__ __forceinline__ float finish_ss(int row, int pn, int within, const float* a, const float* b, const Pre& p, const f32x4* g) const {
;     ...
;             for (int j = 0; j < 4; ++j) { h0[j] = p.x[2 * hb][j] + v[j]; h1[j] = p.x[2 * hb + 1][j] + v[4 + j]; ss += h0[j] * h0[j] + h1[j] * h1[j]; o[j] = h0[j] * g[2 * hb][j]; o[4 + j] = h1[j] * g[2 * hb + 1][j]; }
;             float hh[8] = {h0[0], h0[1], h0[2], h0[3], h1[0], h1[1], h1[2], h1[3]};
;             *(u32x4*)(hcopy + (size_t)row * DM + cc) = pack8(hh);
;             *(u32x4*)(hg + (size_t)row * DM + cc) = pack8(o); }
;         return ss;
; __device__ __forceinline__ void run_epi_out(const EpiOut& E, float* ssq, const f32x4 (&acc)[2][2][4][2], const Unit& u, int wr, int wc, int fr, int fq) {
;     ...
;         for (int m = 0; m < 4; ++m) { PG8_GATHER(ai, m); float ss = E.finish_ss(row0 + m * 16, u.pn, within, a, b, pre[m], g);
;             ss += __shfl_xor(ss, 16); ss += __shfl_xor(ss, 32);
;             if (fq == 0) ssq[(size_t)(row0 + m * 16) * 32 + u.pn * 4 + wc] = ss; } }
	v_lshlrev_b64 v[50:51], 7, v[134:135]
	v_lshl_add_u64 v[50:51], s[24:25], 0, v[50:51]
	s_waitcnt lgkmcnt(0)
	v_add_f32_e32 v48, v48, v49
	global_store_dword v[50:51], v48, off
.LBB0_520:
	s_or_b64 exec, exec, s[26:27]
	s_waitcnt vmcnt(15)
	v_pk_add_f32 v[50:51], v[42:43], v[122:123]
	v_pk_add_f32 v[42:43], v[40:41], v[120:121]
	s_waitcnt vmcnt(14)
	v_pk_add_f32 v[46:47], v[46:47], v[126:127]
	v_pk_add_f32 v[44:45], v[44:45], v[124:125]
	v_pk_mul_f32 v[40:41], v[50:51], v[50:51]
	v_pk_mul_f32 v[52:53], v[42:43], v[42:43]
	s_waitcnt lgkmcnt(0)
	v_pk_mul_f32 v[48:49], v[116:117], v[44:45]
	v_pk_fma_f32 v[54:55], v[46:47], v[46:47], v[40:41]
	v_pk_fma_f32 v[52:53], v[44:45], v[44:45], v[52:53]
	v_cvt_pk_bf16_f32 v40, v44, v45
	v_lshlrev_b64 v[44:45], 12, v[132:133]
	v_pk_mul_f32 v[58:59], v[118:119], v[46:47]
	v_cvt_pk_bf16_f32 v41, v46, v47
	v_lshl_add_u64 v[46:47], s[10:11], 0, v[44:45]
	v_pk_mul_f32 v[56:57], v[112:113], v[42:43]
	v_pk_mul_f32 v[60:61], v[114:115], v[50:51]
	v_cvt_pk_bf16_f32 v42, v42, v43
	v_cvt_pk_bf16_f32 v43, v50, v51
	v_lshl_add_u64 v[46:47], v[46:47], 0, v[208:209]
	v_lshl_add_u64 v[44:45], s[8:9], 0, v[44:45]
	global_store_dwordx4 v[46:47], v[40:43], off
	v_lshl_add_u64 v[44:45], v[44:45], 0, v[208:209]
	v_add_f32_e32 v52, v52, v53
	v_cvt_pk_bf16_f32 v40, v48, v49
	v_cvt_pk_bf16_f32 v41, v58, v59
	v_cvt_pk_bf16_f32 v42, v56, v57
	v_cvt_pk_bf16_f32 v43, v60, v61
	global_store_dwordx4 v[44:45], v[40:43], off
	s_waitcnt vmcnt(14)
	v_pk_add_f32 v[36:37], v[36:37], v[108:109]
	v_add_f32_e32 v52, v54, v52
	v_pk_add_f32 v[42:43], v[34:35], v[98:99]
	v_pk_add_f32 v[34:35], v[32:33], v[96:97]
	v_add_f32_e32 v52, v55, v52
	v_pk_mul_f32 v[48:49], v[34:35], v[34:35]
	v_pk_add_f32 v[38:39], v[38:39], v[110:111]
	v_pk_fma_f32 v[48:49], v[36:37], v[36:37], v[48:49]
	v_pk_mul_f32 v[32:33], v[42:43], v[42:43]
	v_add_f32_e32 v48, v48, v52
	v_pk_fma_f32 v[32:33], v[38:39], v[38:39], v[32:33]
	v_add_f32_e32 v48, v49, v48
	v_add_f32_e32 v32, v32, v48
	v_add_f32_e32 v52, v33, v32
	v_pk_mul_f32 v[40:41], v[104:105], v[36:37]
	v_cvt_pk_bf16_f32 v32, v36, v37
	v_mov_b32_e32 v36, v52
	s_nop 1
	v_permlane16_swap_b32_e32 v36, v52
	v_pk_mul_f32 v[50:51], v[100:101], v[34:35]
	v_cvt_pk_bf16_f32 v33, v38, v39
	v_cvt_pk_bf16_f32 v34, v34, v35
	v_cvt_pk_bf16_f32 v35, v42, v43
	global_store_dwordx4 v[46:47], v[32:35], off offset:256
	v_pk_mul_f32 v[56:57], v[106:107], v[38:39]
	v_pk_mul_f32 v[48:49], v[102:103], v[42:43]
	s_waitcnt lgkmcnt(0)
	v_add_f32_e32 v32, v52, v36
	v_mov_b32_e32 v33, v32
	s_nop 1
	v_permlane32_swap_b32_e32 v33, v32
	v_cvt_pk_bf16_f32 v34, v40, v41
	v_cvt_pk_bf16_f32 v35, v56, v57
	v_cvt_pk_bf16_f32 v36, v50, v51
	v_cvt_pk_bf16_f32 v37, v48, v49
	global_store_dwordx4 v[44:45], v[34:37], off offset:256
	s_and_saveexec_b64 s[26:27], vcc
	s_cbranch_execz .LBB0_522
	v_lshlrev_b64 v[34:35], 7, v[132:133]
	v_lshl_add_u64 v[34:35], s[24:25], 0, v[34:35]
	s_waitcnt lgkmcnt(0)
	v_add_f32_e32 v32, v32, v33
	global_store_dword v[34:35], v32, off
; __device__ __forceinline__ u32x4 pack8(const float* v) { u32x4 w; w.x = cvt_pk_bf16(v[0], v[1]); w.y = cvt_pk_bf16(v[2], v[3]); w.z = cvt_pk_bf16(v[4], v[5]); w.w = cvt_pk_bf16(v[6], v[7]); return w; }
; #define PG8_GATHER(ai, m) float a[8], b[8]; _Pragma("unroll") for (int j = 0; j < 4; ++j) { a[j] = acc[ai][0][m][0][j]; a[4 + j] = acc[ai][0][m][1][j]; b[j] = acc[ai][1][m][0][j]; b[4 + j] = acc[ai][1][m][1][j]; }
;     __device__ __forceinline__ float finish_ss(int row, int pn, int within, const float* a, const float* b, const Pre& p, const f32x4* g) const {
;     ...
;             for (int j = 0; j < 4; ++j) { h0[j] = p.x[2 * hb][j] + v[j]; h1[j] = p.x[2 * hb + 1][j] + v[4 + j]; ss += h0[j] * h0[j] + h1[j] * h1[j]; o[j] = h0[j] * g[2 * hb][j]; o[4 + j] = h1[j] * g[2 * hb + 1][j]; }
;             float hh[8] = {h0[0], h0[1], h0[2], h0[3], h1[0], h1[1], h1[2], h1[3]};
;             *(u32x4*)(hcopy + (size_t)row * DM + cc) = pack8(hh);
;             *(u32x4*)(hg + (size_t)row * DM + cc) = pack8(o); }
;         return ss;
; __device__ __forceinline__ void run_epi_out(const EpiOut& E, float* ssq, const f32x4 (&acc)[2][2][4][2], const Unit& u, int wr, int wc, int fr, int fq) {
;     ...
;         for (int m = 0; m < 4; ++m) { PG8_GATHER(ai, m); float ss = E.finish_ss(row0 + m * 16, u.pn, within, a, b, pre[m], g);
;             ss += __shfl_xor(ss, 16); ss += __shfl_xor(ss, 32);
;             if (fq == 0) ssq[(size_t)(row0 + m * 16) * 32 + u.pn * 4 + wc] = ss; } }
.LBB0_522:
	s_or_b64 exec, exec, s[26:27]
	s_waitcnt vmcnt(15)
	v_pk_add_f32 v[34:35], v[26:27], v[90:91]
	v_pk_add_f32 v[26:27], v[24:25], v[88:89]
	s_waitcnt vmcnt(14)
	v_pk_add_f32 v[30:31], v[30:31], v[94:95]
	v_pk_add_f32 v[28:29], v[28:29], v[92:93]
	v_pk_mul_f32 v[24:25], v[34:35], v[34:35]
	v_pk_mul_f32 v[36:37], v[26:27], v[26:27]
	s_waitcnt lgkmcnt(0)
	v_pk_mul_f32 v[32:33], v[116:117], v[28:29]
	v_pk_fma_f32 v[38:39], v[30:31], v[30:31], v[24:25]
	v_pk_fma_f32 v[36:37], v[28:29], v[28:29], v[36:37]
	v_cvt_pk_bf16_f32 v24, v28, v29
	v_lshlrev_b64 v[28:29], 12, v[130:131]
	v_pk_mul_f32 v[42:43], v[118:119], v[30:31]
	v_cvt_pk_bf16_f32 v25, v30, v31
	v_lshl_add_u64 v[30:31], s[10:11], 0, v[28:29]
	v_pk_mul_f32 v[40:41], v[112:113], v[26:27]
	v_pk_mul_f32 v[44:45], v[114:115], v[34:35]
	v_cvt_pk_bf16_f32 v26, v26, v27
	v_cvt_pk_bf16_f32 v27, v34, v35
	v_lshl_add_u64 v[30:31], v[30:31], 0, v[208:209]
	v_lshl_add_u64 v[28:29], s[8:9], 0, v[28:29]
	global_store_dwordx4 v[30:31], v[24:27], off
	v_lshl_add_u64 v[28:29], v[28:29], 0, v[208:209]
	v_add_f32_e32 v36, v36, v37
	v_cvt_pk_bf16_f32 v24, v32, v33
	v_cvt_pk_bf16_f32 v25, v42, v43
	v_cvt_pk_bf16_f32 v26, v40, v41
	v_cvt_pk_bf16_f32 v27, v44, v45
	global_store_dwordx4 v[28:29], v[24:27], off
	s_waitcnt vmcnt(14)
	v_pk_add_f32 v[20:21], v[20:21], v[84:85]
	v_add_f32_e32 v36, v38, v36
	v_pk_add_f32 v[26:27], v[18:19], v[82:83]
	v_pk_add_f32 v[18:19], v[16:17], v[80:81]
	v_add_f32_e32 v36, v39, v36
	v_pk_mul_f32 v[32:33], v[18:19], v[18:19]
	v_pk_add_f32 v[22:23], v[22:23], v[86:87]
	v_pk_fma_f32 v[32:33], v[20:21], v[20:21], v[32:33]
	v_pk_mul_f32 v[16:17], v[26:27], v[26:27]
	v_add_f32_e32 v32, v32, v36
	v_pk_fma_f32 v[16:17], v[22:23], v[22:23], v[16:17]
	v_add_f32_e32 v32, v33, v32
	v_add_f32_e32 v16, v16, v32
	v_add_f32_e32 v36, v17, v16
	v_pk_mul_f32 v[24:25], v[104:105], v[20:21]
	v_cvt_pk_bf16_f32 v16, v20, v21
	v_mov_b32_e32 v20, v36
	s_nop 1
	v_permlane16_swap_b32_e32 v20, v36
	v_pk_mul_f32 v[34:35], v[100:101], v[18:19]
	v_cvt_pk_bf16_f32 v17, v22, v23
	v_cvt_pk_bf16_f32 v18, v18, v19
	v_cvt_pk_bf16_f32 v19, v26, v27
	global_store_dwordx4 v[30:31], v[16:19], off offset:256
	v_pk_mul_f32 v[40:41], v[106:107], v[22:23]
	v_pk_mul_f32 v[32:33], v[102:103], v[26:27]
	s_waitcnt lgkmcnt(0)
	v_add_f32_e32 v16, v36, v20
	v_mov_b32_e32 v17, v16
	s_nop 1
	v_permlane32_swap_b32_e32 v17, v16
	v_cvt_pk_bf16_f32 v18, v24, v25
	v_cvt_pk_bf16_f32 v19, v40, v41
	v_cvt_pk_bf16_f32 v20, v34, v35
	v_cvt_pk_bf16_f32 v21, v32, v33
	global_store_dwordx4 v[28:29], v[18:21], off offset:256
	s_and_saveexec_b64 s[26:27], vcc
	s_cbranch_execz .LBB0_524
	v_lshlrev_b64 v[18:19], 7, v[130:131]
	v_lshl_add_u64 v[18:19], s[24:25], 0, v[18:19]
	s_waitcnt lgkmcnt(0)
	v_add_f32_e32 v16, v16, v17
	global_store_dword v[18:19], v16, off
.LBB0_524:
	s_or_b64 exec, exec, s[26:27]
	s_waitcnt vmcnt(15)
	v_pk_add_f32 v[18:19], v[10:11], v[74:75]
	v_pk_add_f32 v[10:11], v[8:9], v[72:73]
	s_waitcnt vmcnt(14)
	v_pk_add_f32 v[14:15], v[14:15], v[78:79]
	v_pk_add_f32 v[12:13], v[12:13], v[76:77]
	v_pk_mul_f32 v[8:9], v[18:19], v[18:19]
	v_pk_mul_f32 v[20:21], v[10:11], v[10:11]
	s_waitcnt lgkmcnt(0)
	v_pk_mul_f32 v[16:17], v[116:117], v[12:13]
	v_pk_fma_f32 v[22:23], v[14:15], v[14:15], v[8:9]
	v_pk_fma_f32 v[20:21], v[12:13], v[12:13], v[20:21]
	v_cvt_pk_bf16_f32 v8, v12, v13
	v_lshlrev_b64 v[12:13], 12, v[128:129]
	v_pk_mul_f32 v[26:27], v[118:119], v[14:15]
	v_cvt_pk_bf16_f32 v9, v14, v15
	v_lshl_add_u64 v[14:15], s[10:11], 0, v[12:13]
	v_pk_mul_f32 v[24:25], v[112:113], v[10:11]
	v_pk_mul_f32 v[28:29], v[114:115], v[18:19]
	v_cvt_pk_bf16_f32 v10, v10, v11
	v_cvt_pk_bf16_f32 v11, v18, v19
	v_lshl_add_u64 v[14:15], v[14:15], 0, v[208:209]
	v_lshl_add_u64 v[12:13], s[8:9], 0, v[12:13]
	global_store_dwordx4 v[14:15], v[8:11], off
	v_lshl_add_u64 v[12:13], v[12:13], 0, v[208:209]
	v_add_f32_e32 v20, v20, v21
	v_cvt_pk_bf16_f32 v8, v16, v17
	v_cvt_pk_bf16_f32 v9, v26, v27
	v_cvt_pk_bf16_f32 v10, v24, v25
	v_cvt_pk_bf16_f32 v11, v28, v29
	global_store_dwordx4 v[12:13], v[8:11], off
	s_waitcnt vmcnt(14)
	v_pk_add_f32 v[4:5], v[4:5], v[68:69]
	v_add_f32_e32 v20, v22, v20
	v_pk_add_f32 v[10:11], v[2:3], v[66:67]
	v_pk_add_f32 v[2:3], v[0:1], v[64:65]
	v_add_f32_e32 v20, v23, v20
	v_pk_mul_f32 v[16:17], v[2:3], v[2:3]
	v_pk_add_f32 v[6:7], v[6:7], v[70:71]
	v_pk_fma_f32 v[16:17], v[4:5], v[4:5], v[16:17]
	v_pk_mul_f32 v[0:1], v[10:11], v[10:11]
	v_add_f32_e32 v16, v16, v20
	v_pk_fma_f32 v[0:1], v[6:7], v[6:7], v[0:1]
	v_add_f32_e32 v16, v17, v16
	v_add_f32_e32 v0, v0, v16
	v_add_f32_e32 v20, v1, v0
	v_pk_mul_f32 v[8:9], v[104:105], v[4:5]
	v_cvt_pk_bf16_f32 v0, v4, v5
	v_mov_b32_e32 v4, v20
	s_nop 1
	v_permlane16_swap_b32_e32 v4, v20
	v_pk_mul_f32 v[18:19], v[100:101], v[2:3]
	v_cvt_pk_bf16_f32 v1, v6, v7
	v_cvt_pk_bf16_f32 v2, v2, v3
	v_cvt_pk_bf16_f32 v3, v10, v11
	global_store_dwordx4 v[14:15], v[0:3], off offset:256
	v_pk_mul_f32 v[24:25], v[106:107], v[6:7]
	v_pk_mul_f32 v[16:17], v[102:103], v[10:11]
	s_waitcnt lgkmcnt(0)
	v_add_f32_e32 v0, v20, v4
	v_mov_b32_e32 v1, v0
	s_nop 1
	v_permlane32_swap_b32_e32 v1, v0
	v_cvt_pk_bf16_f32 v2, v8, v9
	v_cvt_pk_bf16_f32 v3, v24, v25
	v_cvt_pk_bf16_f32 v4, v18, v19
	v_cvt_pk_bf16_f32 v5, v16, v17
	global_store_dwordx4 v[12:13], v[2:5], off offset:256
	s_and_saveexec_b64 s[26:27], vcc
	s_cbranch_execz .LBB0_526
	v_lshlrev_b64 v[2:3], 7, v[128:129]
	v_lshl_add_u64 v[2:3], s[24:25], 0, v[2:3]
	s_waitcnt lgkmcnt(0)
	v_add_f32_e32 v0, v0, v1
	global_store_dword v[2:3], v0, off
